# attention: K and V^T tile staging loads (8 per item) issued together instead of one round trip each
# speedup vs baseline: 1.0139x; 1.0031x over previous
; __device__ __forceinline__ void attn_phase(unsigned char* smem, const Params& P, int layer) {
;     ...
;     for (int item = blockIdx.x; item < 512; item += gridDim.x) {
;         const int b = item >> 7, blk = (item & 127) >> 1, kvh = item & 1, s0 = blk * 128;
;         __syncthreads();
;         for (int pc = tid; pc < 2048; pc += 512) { const int key = pc >> 3, d8 = pc & 7, s = s0 - 128 + key; u32x4 v = {0u, 0u, 0u, 0u};
;             if (s >= 0) v = *(const u32x4*)(zb + ((size_t)(b * SEQ + s)) * ZW + 2560 + kvh * 64 + d8 * 8);
;             *(u32x4*)(Kl + key * 72 + d8 * 8) = v; }
;         for (int pc = tid; pc < 2048; pc += 512) { const int d = pc >> 5, k8 = pc & 31, s = s0 - 128 + k8 * 8; u32x4 v = {0u, 0u, 0u, 0u};
;             if (s >= 0) v = *(const u32x4*)(vT + ((size_t)(b * 128 + kvh * 64 + d)) * SEQ + s);
;             *(u32x4*)(Vl + d * 264 + k8 * 8) = v; }
;         Bl[tid] = biasd[(kvh * 4 + (tid >> 7)) * 128 + (tid & 127)];
;         __syncthreads();
.LBB0_489:
	v_readlane_b32 s4, v230, 21
	s_ashr_i32 s6, s33, 7
	v_readlane_b32 s5, v230, 22
	s_waitcnt vmcnt(0)
	s_barrier
	s_and_saveexec_b64 s[2:3], s[4:5]
	s_xor_b64 s[2:3], exec, s[2:3]
	s_lshl_b32 s7, s6, 13
	s_or_saveexec_b64 s[2:3], s[2:3]
	s_bfe_u32 s10, s33, 0x60001
	s_and_b32 s12, s33, 1
	s_lshl_b32 s11, s10, 7
	v_mov_b32_e32 v8, s7
	s_movk_i32 s4, 0x90
	s_xor_b64 exec, exec, s[2:3]
	s_cbranch_execz .LBB0_501
	s_add_i32 s14, s11, 0xffffff80
	s_lshl_b32 s13, s6, 13
	s_lshl_b32 s15, s12, 6
	s_lshl_b32 s74, s15, 1
	v_ashrrev_i32_e32 v13, 3, v3
	v_add_u32_e32 v16, 0, v13
	v_mad_u32_u24 v156, v16, s4, v2
	v_add_u32_e32 v14, s14, v16
	v_mov_b32_e32 v124, 0
	v_mov_b32_e32 v125, 0
	v_mov_b32_e32 v126, 0
	v_mov_b32_e32 v127, 0
	v_cmp_lt_i32_e32 vcc, -1, v14
	s_and_saveexec_b64 s[8:9], vcc
	s_cbranch_execz .Lattn_k0
	v_add_u32_e32 v10, s13, v14
	v_mov_b64_e32 v[8:9], s[86:87]
	v_mad_i64_i32 v[8:9], s[16:17], v10, s76, v[8:9]
	v_lshl_add_u64 v[8:9], v[8:9], 0, s[74:75]
	v_lshl_add_u64 v[8:9], v[8:9], 0, v[0:1]
	v_add_co_u32_e32 v8, vcc, 0x1000, v8
	s_nop 1
	v_addc_co_u32_e32 v9, vcc, 0, v9, vcc
	global_load_dwordx4 v[124:127], v[8:9], off offset:1024
.Lattn_k0:
	s_or_b64 exec, exec, s[8:9]
	v_add_u32_e32 v16, 64, v13
	v_mad_u32_u24 v157, v16, s4, v2
	v_add_u32_e32 v14, s14, v16
	v_mov_b32_e32 v128, 0
	v_mov_b32_e32 v129, 0
	v_mov_b32_e32 v130, 0
	v_mov_b32_e32 v131, 0
	v_cmp_lt_i32_e32 vcc, -1, v14
	s_and_saveexec_b64 s[8:9], vcc
	s_cbranch_execz .Lattn_k1
	v_add_u32_e32 v10, s13, v14
	v_mov_b64_e32 v[8:9], s[86:87]
	v_mad_i64_i32 v[8:9], s[16:17], v10, s76, v[8:9]
	v_lshl_add_u64 v[8:9], v[8:9], 0, s[74:75]
	v_lshl_add_u64 v[8:9], v[8:9], 0, v[0:1]
	v_add_co_u32_e32 v8, vcc, 0x1000, v8
	s_nop 1
	v_addc_co_u32_e32 v9, vcc, 0, v9, vcc
	global_load_dwordx4 v[128:131], v[8:9], off offset:1024
.Lattn_k1:
	s_or_b64 exec, exec, s[8:9]
	v_add_u32_e32 v16, 128, v13
	v_mad_u32_u24 v158, v16, s4, v2
	v_add_u32_e32 v14, s14, v16
	v_mov_b32_e32 v132, 0
	v_mov_b32_e32 v133, 0
	v_mov_b32_e32 v134, 0
	v_mov_b32_e32 v135, 0
	v_cmp_lt_i32_e32 vcc, -1, v14
	s_and_saveexec_b64 s[8:9], vcc
	s_cbranch_execz .Lattn_k2
	v_add_u32_e32 v10, s13, v14
	v_mov_b64_e32 v[8:9], s[86:87]
	v_mad_i64_i32 v[8:9], s[16:17], v10, s76, v[8:9]
	v_lshl_add_u64 v[8:9], v[8:9], 0, s[74:75]
	v_lshl_add_u64 v[8:9], v[8:9], 0, v[0:1]
	v_add_co_u32_e32 v8, vcc, 0x1000, v8
	s_nop 1
	v_addc_co_u32_e32 v9, vcc, 0, v9, vcc
	global_load_dwordx4 v[132:135], v[8:9], off offset:1024
.Lattn_k2:
	s_or_b64 exec, exec, s[8:9]
	v_add_u32_e32 v16, 192, v13
	v_mad_u32_u24 v159, v16, s4, v2
	v_add_u32_e32 v14, s14, v16
	v_mov_b32_e32 v136, 0
	v_mov_b32_e32 v137, 0
	v_mov_b32_e32 v138, 0
	v_mov_b32_e32 v139, 0
	v_cmp_lt_i32_e32 vcc, -1, v14
	s_and_saveexec_b64 s[8:9], vcc
	s_cbranch_execz .Lattn_k3
	v_add_u32_e32 v10, s13, v14
	v_mov_b64_e32 v[8:9], s[86:87]
	v_mad_i64_i32 v[8:9], s[16:17], v10, s76, v[8:9]
	v_lshl_add_u64 v[8:9], v[8:9], 0, s[74:75]
	v_lshl_add_u64 v[8:9], v[8:9], 0, v[0:1]
	v_add_co_u32_e32 v8, vcc, 0x1000, v8
	s_nop 1
	v_addc_co_u32_e32 v9, vcc, 0, v9, vcc
	global_load_dwordx4 v[136:139], v[8:9], off offset:1024
.Lattn_k3:
	s_or_b64 exec, exec, s[8:9]
	s_and_b32 s4, s33, 0xffffff80
	s_or_b32 s15, s15, s4
	s_movk_i32 s4, 0x210
	v_and_b32_e32 v17, 0xf8, v59
	v_add_u32_e32 v12, s14, v17
	v_lshlrev_b32_e32 v15, 1, v17
	v_ashrrev_i32_e32 v16, 5, v3
	v_add_u32_e32 v14, 0, v16
	v_mul_lo_u32 v160, v14, s4
	v_add_u32_e32 v160, v160, v15
	v_mov_b32_e32 v140, 0
	v_mov_b32_e32 v141, 0
	v_mov_b32_e32 v142, 0
	v_mov_b32_e32 v143, 0
	v_cmp_lt_i32_e32 vcc, -1, v12
	s_and_saveexec_b64 s[8:9], vcc
	s_cbranch_execz .Lattn_v0
	v_add_u32_e32 v8, s15, v14
	v_ashrrev_i32_e32 v9, 31, v8
	v_lshlrev_b64 v[8:9], 14, v[8:9]
	v_lshl_add_u64 v[8:9], s[88:89], 0, v[8:9]
	v_mov_b32_e32 v13, v1
	v_lshl_add_u64 v[8:9], v[12:13], 1, v[8:9]
	global_load_dwordx4 v[140:143], v[8:9], off
.Lattn_v0:
	s_or_b64 exec, exec, s[8:9]
	v_add_u32_e32 v14, 16, v16
	v_mul_lo_u32 v161, v14, s4
	v_add_u32_e32 v161, v161, v15
	v_mov_b32_e32 v144, 0
	v_mov_b32_e32 v145, 0
	v_mov_b32_e32 v146, 0
	v_mov_b32_e32 v147, 0
	v_cmp_lt_i32_e32 vcc, -1, v12
	s_and_saveexec_b64 s[8:9], vcc
	s_cbranch_execz .Lattn_v1
	v_add_u32_e32 v8, s15, v14
	v_ashrrev_i32_e32 v9, 31, v8
	v_lshlrev_b64 v[8:9], 14, v[8:9]
	v_lshl_add_u64 v[8:9], s[88:89], 0, v[8:9]
	v_mov_b32_e32 v13, v1
	v_lshl_add_u64 v[8:9], v[12:13], 1, v[8:9]
	global_load_dwordx4 v[144:147], v[8:9], off
.Lattn_v1:
	s_or_b64 exec, exec, s[8:9]
	v_add_u32_e32 v14, 32, v16
	v_mul_lo_u32 v162, v14, s4
	v_add_u32_e32 v162, v162, v15
	v_mov_b32_e32 v148, 0
	v_mov_b32_e32 v149, 0
	v_mov_b32_e32 v150, 0
	v_mov_b32_e32 v151, 0
	v_cmp_lt_i32_e32 vcc, -1, v12
	s_and_saveexec_b64 s[8:9], vcc
	s_cbranch_execz .Lattn_v2
	v_add_u32_e32 v8, s15, v14
	v_ashrrev_i32_e32 v9, 31, v8
	v_lshlrev_b64 v[8:9], 14, v[8:9]
	v_lshl_add_u64 v[8:9], s[88:89], 0, v[8:9]
	v_mov_b32_e32 v13, v1
	v_lshl_add_u64 v[8:9], v[12:13], 1, v[8:9]
	global_load_dwordx4 v[148:151], v[8:9], off
.Lattn_v2:
	s_or_b64 exec, exec, s[8:9]
	v_add_u32_e32 v14, 48, v16
	v_mul_lo_u32 v163, v14, s4
	v_add_u32_e32 v163, v163, v15
	v_mov_b32_e32 v152, 0
	v_mov_b32_e32 v153, 0
	v_mov_b32_e32 v154, 0
	v_mov_b32_e32 v155, 0
	v_cmp_lt_i32_e32 vcc, -1, v12
	s_and_saveexec_b64 s[8:9], vcc
	s_cbranch_execz .Lattn_v3
	v_add_u32_e32 v8, s15, v14
	v_ashrrev_i32_e32 v9, 31, v8
	v_lshlrev_b64 v[8:9], 14, v[8:9]
	v_lshl_add_u64 v[8:9], s[88:89], 0, v[8:9]
	v_mov_b32_e32 v13, v1
	v_lshl_add_u64 v[8:9], v[12:13], 1, v[8:9]
	global_load_dwordx4 v[152:155], v[8:9], off
.Lattn_v3:
	s_or_b64 exec, exec, s[8:9]
	s_waitcnt vmcnt(0)
	ds_write_b128 v156, v[124:127]
	ds_write_b128 v157, v[128:131]
	ds_write_b128 v158, v[132:135]
	ds_write_b128 v159, v[136:139]
	ds_write_b128 v160, v[140:143] offset:36864
	ds_write_b128 v161, v[144:147] offset:36864
	ds_write_b128 v162, v[148:151] offset:36864
	ds_write_b128 v163, v[152:155] offset:36864
	s_mov_b64 s[6:7], exec
	v_mov_b32_e32 v8, s13
